# P10 k-loop: SGPR-base LDS-DMA, LDS operand reads software-pipelined into the MFMA segments (second X register set), per-phase counted vmcnt waits (same scheme as P8)
# speedup vs baseline: 1.0262x; 1.0091x over previous
.LBB0_1296:
	s_add_u32 s28, s28, 0x160080
	s_addc_u32 s29, s29, 0
	s_add_u32 s58, s30, 0x100
	s_addc_u32 s59, s31, 0
	s_mov_b32 s60, -2
	v_add_u32_e32 v154, 0x18000, v173
	v_add_u32_e32 v155, 0x1c000, v173
	ds_read_b128 v[126:129], v175
	ds_read_b128 v[134:137], v175 offset:1024
	ds_read_b128 v[138:141], v175 offset:2048
	ds_read_b128 v[142:145], v175 offset:3072
	ds_read_b128 v[158:161], v176
	ds_read_b128 v[178:181], v176 offset:1024
	ds_read_b128 v[182:185], v176 offset:2048
	ds_read_b128 v[186:189], v176 offset:3072
	ds_read_b128 v[190:193], v176 offset:4096
	ds_read_b128 v[194:197], v176 offset:5120
	ds_read_b128 v[198:201], v176 offset:6144
	ds_read_b128 v[202:205], v176 offset:7168
	s_add_u32 s30, s28, 0xffea0080
	s_addc_u32 s31, s29, -1
	s_cmpk_eq_i32 s60, 0x54
	s_cselect_b32 s35, s7, s31
	s_cselect_b32 s34, s6, s30
	s_cselect_b32 s31, s9, s59
	s_cselect_b32 s30, s8, s58
	s_add_i32 m0, s43, 0xc000
	s_nop 0
	global_load_lds_dwordx4 v150, s[28:29]
	s_add_i32 m0, s43, 0xe000
	s_nop 0
	global_load_lds_dwordx4 v152, s[28:29]
	s_waitcnt vmcnt(10)
	s_barrier
	s_waitcnt lgkmcnt(0)
	s_setprio 1
	v_mfma_f32_16x16x32_bf16 v[130:133], v[126:129], v[158:161], 0
	ds_read_b128 v[206:209], v177
	v_mfma_f32_16x16x32_bf16 v[122:125], v[138:141], v[158:161], 0
	v_mfma_f32_16x16x32_bf16 v[118:121], v[126:129], v[182:185], 0
	v_mfma_f32_16x16x32_bf16 v[114:117], v[138:141], v[182:185], 0
	v_mfma_f32_16x16x32_bf16 v[102:105], v[126:129], v[190:193], 0
	ds_read_b128 v[210:213], v177 offset:1024
	v_mfma_f32_16x16x32_bf16 v[98:101], v[138:141], v[190:193], 0
	v_mfma_f32_16x16x32_bf16 v[86:89], v[126:129], v[198:201], 0
	v_mfma_f32_16x16x32_bf16 v[82:85], v[138:141], v[198:201], 0
	v_mfma_f32_16x16x32_bf16 v[130:133], v[134:137], v[178:181], v[130:133]
	ds_read_b128 v[214:217], v177 offset:2048
	v_mfma_f32_16x16x32_bf16 v[122:125], v[142:145], v[178:181], v[122:125]
	v_mfma_f32_16x16x32_bf16 v[118:121], v[134:137], v[186:189], v[118:121]
	v_mfma_f32_16x16x32_bf16 v[114:117], v[142:145], v[186:189], v[114:117]
	v_mfma_f32_16x16x32_bf16 v[102:105], v[134:137], v[194:197], v[102:105]
	ds_read_b128 v[218:221], v177 offset:3072
	v_mfma_f32_16x16x32_bf16 v[98:101], v[142:145], v[194:197], v[98:101]
	v_mfma_f32_16x16x32_bf16 v[86:89], v[134:137], v[202:205], v[86:89]
	v_mfma_f32_16x16x32_bf16 v[82:85], v[142:145], v[202:205], v[82:85]
	s_setprio 0
	s_barrier
	s_add_i32 s61, s51, s40
	s_add_u32 s96, s30, 0x80
	s_addc_u32 s97, s31, 0
	s_mov_b32 m0, s61
	s_nop 0
	global_load_lds_dwordx4 v146, s[30:31]
	s_add_i32 m0, s61, 0x2000
	s_nop 0
	global_load_lds_dwordx4 v148, s[30:31]
	s_waitcnt vmcnt(10)
	s_barrier
	s_waitcnt lgkmcnt(0)
	s_setprio 1
	v_mfma_f32_16x16x32_bf16 v[110:113], v[206:209], v[158:161], 0
	ds_read_b128 v[226:229], v176 offset:16384
	v_mfma_f32_16x16x32_bf16 v[106:109], v[214:217], v[158:161], 0
	v_mfma_f32_16x16x32_bf16 v[94:97], v[206:209], v[182:185], 0
	ds_read_b128 v[230:233], v176 offset:17408
	v_mfma_f32_16x16x32_bf16 v[90:93], v[214:217], v[182:185], 0
	v_mfma_f32_16x16x32_bf16 v[78:81], v[206:209], v[190:193], 0
	ds_read_b128 v[234:237], v176 offset:18432
	v_mfma_f32_16x16x32_bf16 v[74:77], v[214:217], v[190:193], 0
	v_mfma_f32_16x16x32_bf16 v[70:73], v[206:209], v[198:201], 0
	ds_read_b128 v[238:241], v176 offset:19456
	v_mfma_f32_16x16x32_bf16 v[66:69], v[214:217], v[198:201], 0
	v_mfma_f32_16x16x32_bf16 v[110:113], v[210:213], v[178:181], v[110:113]
	ds_read_b128 v[242:245], v176 offset:20480
	v_mfma_f32_16x16x32_bf16 v[106:109], v[218:221], v[178:181], v[106:109]
	v_mfma_f32_16x16x32_bf16 v[94:97], v[210:213], v[186:189], v[94:97]
	ds_read_b128 v[246:249], v176 offset:21504
	v_mfma_f32_16x16x32_bf16 v[90:93], v[218:221], v[186:189], v[90:93]
	v_mfma_f32_16x16x32_bf16 v[78:81], v[210:213], v[194:197], v[78:81]
	ds_read_b128 v[250:253], v176 offset:22528
	v_mfma_f32_16x16x32_bf16 v[74:77], v[218:221], v[194:197], v[74:77]
	v_mfma_f32_16x16x32_bf16 v[70:73], v[210:213], v[202:205], v[70:73]
	ds_read_b128 v[222:225], v176 offset:23552
	v_mfma_f32_16x16x32_bf16 v[66:69], v[218:221], v[202:205], v[66:69]
	s_setprio 0
	s_barrier
	s_mov_b32 m0, s43
	s_add_u32 s94, s34, 0x80
	s_addc_u32 s95, s35, 0
	global_load_lds_dwordx4 v146, s[34:35]
	s_mov_b32 m0, s44
	s_nop 0
	global_load_lds_dwordx4 v148, s[34:35]
	s_waitcnt vmcnt(8)
	s_barrier
	s_waitcnt lgkmcnt(0)
	s_setprio 1
	v_mfma_f32_16x16x32_bf16 v[62:65], v[126:129], v[226:229], 0
	ds_read_b128 v[158:161], v176 offset:32768
	v_mfma_f32_16x16x32_bf16 v[58:61], v[138:141], v[226:229], 0
	v_mfma_f32_16x16x32_bf16 v[54:57], v[126:129], v[234:237], 0
	ds_read_b128 v[178:181], v176 offset:33792
	v_mfma_f32_16x16x32_bf16 v[46:49], v[138:141], v[234:237], 0
	v_mfma_f32_16x16x32_bf16 v[38:41], v[126:129], v[242:245], 0
	ds_read_b128 v[182:185], v176 offset:34816
	v_mfma_f32_16x16x32_bf16 v[30:33], v[138:141], v[242:245], 0
	v_mfma_f32_16x16x32_bf16 v[22:25], v[126:129], v[250:253], 0
	ds_read_b128 v[186:189], v176 offset:35840
	v_mfma_f32_16x16x32_bf16 v[14:17], v[138:141], v[250:253], 0
	v_mfma_f32_16x16x32_bf16 v[62:65], v[134:137], v[230:233], v[62:65]
	ds_read_b128 v[190:193], v176 offset:36864
	v_mfma_f32_16x16x32_bf16 v[58:61], v[142:145], v[230:233], v[58:61]
	v_mfma_f32_16x16x32_bf16 v[54:57], v[134:137], v[238:241], v[54:57]
	ds_read_b128 v[194:197], v176 offset:37888
	v_mfma_f32_16x16x32_bf16 v[46:49], v[142:145], v[238:241], v[46:49]
	v_mfma_f32_16x16x32_bf16 v[38:41], v[134:137], v[246:249], v[38:41]
	ds_read_b128 v[198:201], v176 offset:38912
	v_mfma_f32_16x16x32_bf16 v[30:33], v[142:145], v[246:249], v[30:33]
	v_mfma_f32_16x16x32_bf16 v[22:25], v[134:137], v[222:225], v[22:25]
	ds_read_b128 v[202:205], v176 offset:39936
	v_mfma_f32_16x16x32_bf16 v[14:17], v[142:145], v[222:225], v[14:17]
	s_setprio 0
	s_barrier
	s_add_u32 s62, s30, 0x160000
	s_addc_u32 s63, s31, 0
	s_add_i32 s61, s52, s40
	s_mov_b32 m0, s61
	s_nop 0
	global_load_lds_dwordx4 v146, s[62:63]
	s_add_i32 m0, s61, 0x2000
	s_nop 0
	global_load_lds_dwordx4 v148, s[62:63]
	s_waitcnt vmcnt(10)
	s_barrier
	s_waitcnt lgkmcnt(0)
	s_setprio 1
	v_mfma_f32_16x16x32_bf16 v[50:53], v[206:209], v[226:229], 0
	ds_read_b128 v[126:129], v154
	v_mfma_f32_16x16x32_bf16 v[42:45], v[214:217], v[226:229], 0
	v_mfma_f32_16x16x32_bf16 v[34:37], v[206:209], v[234:237], 0
	v_mfma_f32_16x16x32_bf16 v[26:29], v[214:217], v[234:237], 0
	v_mfma_f32_16x16x32_bf16 v[18:21], v[206:209], v[242:245], 0
	ds_read_b128 v[134:137], v154 offset:1024
	v_mfma_f32_16x16x32_bf16 v[10:13], v[214:217], v[242:245], 0
	v_mfma_f32_16x16x32_bf16 v[6:9], v[206:209], v[250:253], 0
	v_mfma_f32_16x16x32_bf16 v[2:5], v[214:217], v[250:253], 0
	v_mfma_f32_16x16x32_bf16 v[50:53], v[210:213], v[230:233], v[50:53]
	ds_read_b128 v[138:141], v154 offset:2048
	v_mfma_f32_16x16x32_bf16 v[42:45], v[218:221], v[230:233], v[42:45]
	v_mfma_f32_16x16x32_bf16 v[34:37], v[210:213], v[238:241], v[34:37]
	v_mfma_f32_16x16x32_bf16 v[26:29], v[218:221], v[238:241], v[26:29]
	v_mfma_f32_16x16x32_bf16 v[18:21], v[210:213], v[246:249], v[18:21]
	ds_read_b128 v[142:145], v154 offset:3072
	v_mfma_f32_16x16x32_bf16 v[10:13], v[218:221], v[246:249], v[10:13]
	v_mfma_f32_16x16x32_bf16 v[6:9], v[210:213], v[222:225], v[6:9]
	v_mfma_f32_16x16x32_bf16 v[2:5], v[218:221], v[222:225], v[2:5]
	s_setprio 0
	s_barrier
	s_add_i32 s61, 0, 0x18000
	s_add_u32 s34, s34, 0x160000
	s_addc_u32 s35, s35, 0
	s_mov_b32 m0, s45
	s_nop 0
	global_load_lds_dwordx4 v146, s[34:35]
	s_mov_b32 m0, s46
	s_nop 0
	global_load_lds_dwordx4 v148, s[34:35]
	s_waitcnt vmcnt(10)
	s_barrier
	s_waitcnt lgkmcnt(0)
	s_setprio 1
	v_mfma_f32_16x16x32_bf16 v[130:133], v[126:129], v[158:161], v[130:133]
	ds_read_b128 v[206:209], v155
	v_mfma_f32_16x16x32_bf16 v[122:125], v[138:141], v[158:161], v[122:125]
	v_mfma_f32_16x16x32_bf16 v[118:121], v[126:129], v[182:185], v[118:121]
	v_mfma_f32_16x16x32_bf16 v[114:117], v[138:141], v[182:185], v[114:117]
	v_mfma_f32_16x16x32_bf16 v[102:105], v[126:129], v[190:193], v[102:105]
	ds_read_b128 v[210:213], v155 offset:1024
	v_mfma_f32_16x16x32_bf16 v[98:101], v[138:141], v[190:193], v[98:101]
	v_mfma_f32_16x16x32_bf16 v[86:89], v[126:129], v[198:201], v[86:89]
	v_mfma_f32_16x16x32_bf16 v[82:85], v[138:141], v[198:201], v[82:85]
	v_mfma_f32_16x16x32_bf16 v[130:133], v[134:137], v[178:181], v[130:133]
	ds_read_b128 v[214:217], v155 offset:2048
	v_mfma_f32_16x16x32_bf16 v[122:125], v[142:145], v[178:181], v[122:125]
	v_mfma_f32_16x16x32_bf16 v[118:121], v[134:137], v[186:189], v[118:121]
	v_mfma_f32_16x16x32_bf16 v[114:117], v[142:145], v[186:189], v[114:117]
	v_mfma_f32_16x16x32_bf16 v[102:105], v[134:137], v[194:197], v[102:105]
	ds_read_b128 v[218:221], v155 offset:3072
	v_mfma_f32_16x16x32_bf16 v[98:101], v[142:145], v[194:197], v[98:101]
	v_mfma_f32_16x16x32_bf16 v[86:89], v[134:137], v[202:205], v[86:89]
	v_mfma_f32_16x16x32_bf16 v[82:85], v[142:145], v[202:205], v[82:85]
	s_setprio 0
	s_barrier
	s_add_i32 s84, 0, 0x1c000
	s_add_i32 s85, s61, s40
	s_mov_b32 m0, s85
	s_nop 0
	global_load_lds_dwordx4 v146, s[96:97]
	s_add_i32 m0, s85, 0x2000
	s_nop 0
	global_load_lds_dwordx4 v148, s[96:97]
	s_waitcnt vmcnt(10)
	s_barrier
	s_waitcnt lgkmcnt(0)
	s_setprio 1
	v_mfma_f32_16x16x32_bf16 v[110:113], v[206:209], v[158:161], v[110:113]
	ds_read_b128 v[226:229], v176 offset:49152
	v_mfma_f32_16x16x32_bf16 v[106:109], v[214:217], v[158:161], v[106:109]
	v_mfma_f32_16x16x32_bf16 v[94:97], v[206:209], v[182:185], v[94:97]
	ds_read_b128 v[230:233], v176 offset:50176
	v_mfma_f32_16x16x32_bf16 v[90:93], v[214:217], v[182:185], v[90:93]
	v_mfma_f32_16x16x32_bf16 v[78:81], v[206:209], v[190:193], v[78:81]
	ds_read_b128 v[234:237], v176 offset:51200
	v_mfma_f32_16x16x32_bf16 v[74:77], v[214:217], v[190:193], v[74:77]
	v_mfma_f32_16x16x32_bf16 v[70:73], v[206:209], v[198:201], v[70:73]
	ds_read_b128 v[238:241], v176 offset:52224
	v_mfma_f32_16x16x32_bf16 v[66:69], v[214:217], v[198:201], v[66:69]
	v_mfma_f32_16x16x32_bf16 v[110:113], v[210:213], v[178:181], v[110:113]
	ds_read_b128 v[242:245], v176 offset:53248
	v_mfma_f32_16x16x32_bf16 v[106:109], v[218:221], v[178:181], v[106:109]
	v_mfma_f32_16x16x32_bf16 v[94:97], v[210:213], v[186:189], v[94:97]
	ds_read_b128 v[246:249], v176 offset:54272
	v_mfma_f32_16x16x32_bf16 v[90:93], v[218:221], v[186:189], v[90:93]
	v_mfma_f32_16x16x32_bf16 v[78:81], v[210:213], v[194:197], v[78:81]
	ds_read_b128 v[250:253], v176 offset:55296
	v_mfma_f32_16x16x32_bf16 v[74:77], v[218:221], v[194:197], v[74:77]
	v_mfma_f32_16x16x32_bf16 v[70:73], v[210:213], v[202:205], v[70:73]
	ds_read_b128 v[222:225], v176 offset:56320
	v_mfma_f32_16x16x32_bf16 v[66:69], v[218:221], v[202:205], v[66:69]
	s_setprio 0
	s_barrier
	s_mov_b32 m0, s48
	s_nop 0
	global_load_lds_dwordx4 v146, s[94:95]
	s_mov_b32 m0, s49
	s_nop 0
	global_load_lds_dwordx4 v148, s[94:95]
	s_waitcnt vmcnt(8)
	s_barrier
	s_waitcnt lgkmcnt(0)
	s_setprio 1
	v_mfma_f32_16x16x32_bf16 v[62:65], v[126:129], v[226:229], v[62:65]
	ds_read_b128 v[158:161], v176
	v_mfma_f32_16x16x32_bf16 v[58:61], v[138:141], v[226:229], v[58:61]
	v_mfma_f32_16x16x32_bf16 v[54:57], v[126:129], v[234:237], v[54:57]
	ds_read_b128 v[178:181], v176 offset:1024
	v_mfma_f32_16x16x32_bf16 v[46:49], v[138:141], v[234:237], v[46:49]
	v_mfma_f32_16x16x32_bf16 v[38:41], v[126:129], v[242:245], v[38:41]
	ds_read_b128 v[182:185], v176 offset:2048
	v_mfma_f32_16x16x32_bf16 v[30:33], v[138:141], v[242:245], v[30:33]
	v_mfma_f32_16x16x32_bf16 v[22:25], v[126:129], v[250:253], v[22:25]
	ds_read_b128 v[186:189], v176 offset:3072
	v_mfma_f32_16x16x32_bf16 v[14:17], v[138:141], v[250:253], v[14:17]
	v_mfma_f32_16x16x32_bf16 v[62:65], v[134:137], v[230:233], v[62:65]
	ds_read_b128 v[190:193], v176 offset:4096
	v_mfma_f32_16x16x32_bf16 v[58:61], v[142:145], v[230:233], v[58:61]
	v_mfma_f32_16x16x32_bf16 v[54:57], v[134:137], v[238:241], v[54:57]
	ds_read_b128 v[194:197], v176 offset:5120
	v_mfma_f32_16x16x32_bf16 v[46:49], v[142:145], v[238:241], v[46:49]
	v_mfma_f32_16x16x32_bf16 v[38:41], v[134:137], v[246:249], v[38:41]
	ds_read_b128 v[198:201], v176 offset:6144
	v_mfma_f32_16x16x32_bf16 v[30:33], v[142:145], v[246:249], v[30:33]
	v_mfma_f32_16x16x32_bf16 v[22:25], v[134:137], v[222:225], v[22:25]
	ds_read_b128 v[202:205], v176 offset:7168
	v_mfma_f32_16x16x32_bf16 v[14:17], v[142:145], v[222:225], v[14:17]
	s_setprio 0
	s_barrier
	s_add_u32 s30, s30, 0x160080
	s_addc_u32 s31, s31, 0
	s_add_i32 s84, s84, s40
	s_mov_b32 m0, s84
	s_nop 0
	global_load_lds_dwordx4 v146, s[30:31]
	s_add_i32 m0, s84, 0x2000
	s_nop 0
	global_load_lds_dwordx4 v148, s[30:31]
	s_waitcnt vmcnt(10)
	s_barrier
	s_waitcnt lgkmcnt(0)
	s_setprio 1
	v_mfma_f32_16x16x32_bf16 v[50:53], v[206:209], v[226:229], v[50:53]
	ds_read_b128 v[126:129], v175
	v_mfma_f32_16x16x32_bf16 v[42:45], v[214:217], v[226:229], v[42:45]
	v_mfma_f32_16x16x32_bf16 v[34:37], v[206:209], v[234:237], v[34:37]
	v_mfma_f32_16x16x32_bf16 v[26:29], v[214:217], v[234:237], v[26:29]
	v_mfma_f32_16x16x32_bf16 v[18:21], v[206:209], v[242:245], v[18:21]
	ds_read_b128 v[134:137], v175 offset:1024
	v_mfma_f32_16x16x32_bf16 v[10:13], v[214:217], v[242:245], v[10:13]
	v_mfma_f32_16x16x32_bf16 v[6:9], v[206:209], v[250:253], v[6:9]
	v_mfma_f32_16x16x32_bf16 v[2:5], v[214:217], v[250:253], v[2:5]
	v_mfma_f32_16x16x32_bf16 v[50:53], v[210:213], v[230:233], v[50:53]
	ds_read_b128 v[138:141], v175 offset:2048
	v_mfma_f32_16x16x32_bf16 v[42:45], v[218:221], v[230:233], v[42:45]
	v_mfma_f32_16x16x32_bf16 v[34:37], v[210:213], v[238:241], v[34:37]
	v_mfma_f32_16x16x32_bf16 v[26:29], v[218:221], v[238:241], v[26:29]
	v_mfma_f32_16x16x32_bf16 v[18:21], v[210:213], v[246:249], v[18:21]
	ds_read_b128 v[142:145], v175 offset:3072
	v_mfma_f32_16x16x32_bf16 v[10:13], v[218:221], v[246:249], v[10:13]
	v_mfma_f32_16x16x32_bf16 v[6:9], v[210:213], v[222:225], v[6:9]
	v_mfma_f32_16x16x32_bf16 v[2:5], v[218:221], v[222:225], v[2:5]
	s_setprio 0
	s_add_i32 s60, s60, 2
	s_add_u32 s28, s28, 0x100
	s_addc_u32 s29, s29, 0
	s_add_u32 s58, s58, 0x100
	s_addc_u32 s59, s59, 0
	s_cmpk_gt_u32 s60, 0x55
	s_barrier
	s_cbranch_scc0 .LBB0_1297
	s_branch .Lp10_loop_exit
.LBB0_1297:
	s_add_u32 s30, s28, 0xffea0080
	s_addc_u32 s31, s29, -1
	s_cmpk_eq_i32 s60, 0x54
	s_cselect_b32 s35, s7, s31
	s_cselect_b32 s34, s6, s30
	s_cselect_b32 s31, s9, s59
	s_cselect_b32 s30, s8, s58
	s_add_i32 m0, s43, 0xc000
	s_nop 0
	global_load_lds_dwordx4 v150, s[28:29]
	s_add_i32 m0, s43, 0xe000
	s_nop 0
	global_load_lds_dwordx4 v152, s[28:29]
	s_waitcnt vmcnt(10)
	s_barrier
	s_waitcnt lgkmcnt(0)
	s_setprio 1
	v_mfma_f32_16x16x32_bf16 v[130:133], v[126:129], v[158:161], v[130:133]
	ds_read_b128 v[206:209], v177
	v_mfma_f32_16x16x32_bf16 v[122:125], v[138:141], v[158:161], v[122:125]
	v_mfma_f32_16x16x32_bf16 v[118:121], v[126:129], v[182:185], v[118:121]
	v_mfma_f32_16x16x32_bf16 v[114:117], v[138:141], v[182:185], v[114:117]
	v_mfma_f32_16x16x32_bf16 v[102:105], v[126:129], v[190:193], v[102:105]
	ds_read_b128 v[210:213], v177 offset:1024
	v_mfma_f32_16x16x32_bf16 v[98:101], v[138:141], v[190:193], v[98:101]
	v_mfma_f32_16x16x32_bf16 v[86:89], v[126:129], v[198:201], v[86:89]
	v_mfma_f32_16x16x32_bf16 v[82:85], v[138:141], v[198:201], v[82:85]
	v_mfma_f32_16x16x32_bf16 v[130:133], v[134:137], v[178:181], v[130:133]
	ds_read_b128 v[214:217], v177 offset:2048
	v_mfma_f32_16x16x32_bf16 v[122:125], v[142:145], v[178:181], v[122:125]
	v_mfma_f32_16x16x32_bf16 v[118:121], v[134:137], v[186:189], v[118:121]
	v_mfma_f32_16x16x32_bf16 v[114:117], v[142:145], v[186:189], v[114:117]
	v_mfma_f32_16x16x32_bf16 v[102:105], v[134:137], v[194:197], v[102:105]
	ds_read_b128 v[218:221], v177 offset:3072
	v_mfma_f32_16x16x32_bf16 v[98:101], v[142:145], v[194:197], v[98:101]
	v_mfma_f32_16x16x32_bf16 v[86:89], v[134:137], v[202:205], v[86:89]
	v_mfma_f32_16x16x32_bf16 v[82:85], v[142:145], v[202:205], v[82:85]
	s_setprio 0
	s_barrier
	s_add_i32 s61, s51, s40
	s_add_u32 s96, s30, 0x80
	s_addc_u32 s97, s31, 0
	s_mov_b32 m0, s61
	s_nop 0
	global_load_lds_dwordx4 v146, s[30:31]
	s_add_i32 m0, s61, 0x2000
	s_nop 0
	global_load_lds_dwordx4 v148, s[30:31]
	s_waitcnt vmcnt(10)
	s_barrier
	s_waitcnt lgkmcnt(0)
	s_setprio 1
	v_mfma_f32_16x16x32_bf16 v[110:113], v[206:209], v[158:161], v[110:113]
	ds_read_b128 v[226:229], v176 offset:16384
	v_mfma_f32_16x16x32_bf16 v[106:109], v[214:217], v[158:161], v[106:109]
	v_mfma_f32_16x16x32_bf16 v[94:97], v[206:209], v[182:185], v[94:97]
	ds_read_b128 v[230:233], v176 offset:17408
	v_mfma_f32_16x16x32_bf16 v[90:93], v[214:217], v[182:185], v[90:93]
	v_mfma_f32_16x16x32_bf16 v[78:81], v[206:209], v[190:193], v[78:81]
	ds_read_b128 v[234:237], v176 offset:18432
	v_mfma_f32_16x16x32_bf16 v[74:77], v[214:217], v[190:193], v[74:77]
	v_mfma_f32_16x16x32_bf16 v[70:73], v[206:209], v[198:201], v[70:73]
	ds_read_b128 v[238:241], v176 offset:19456
	v_mfma_f32_16x16x32_bf16 v[66:69], v[214:217], v[198:201], v[66:69]
	v_mfma_f32_16x16x32_bf16 v[110:113], v[210:213], v[178:181], v[110:113]
	ds_read_b128 v[242:245], v176 offset:20480
	v_mfma_f32_16x16x32_bf16 v[106:109], v[218:221], v[178:181], v[106:109]
	v_mfma_f32_16x16x32_bf16 v[94:97], v[210:213], v[186:189], v[94:97]
	ds_read_b128 v[246:249], v176 offset:21504
	v_mfma_f32_16x16x32_bf16 v[90:93], v[218:221], v[186:189], v[90:93]
	v_mfma_f32_16x16x32_bf16 v[78:81], v[210:213], v[194:197], v[78:81]
	ds_read_b128 v[250:253], v176 offset:22528
	v_mfma_f32_16x16x32_bf16 v[74:77], v[218:221], v[194:197], v[74:77]
	v_mfma_f32_16x16x32_bf16 v[70:73], v[210:213], v[202:205], v[70:73]
	ds_read_b128 v[222:225], v176 offset:23552
	v_mfma_f32_16x16x32_bf16 v[66:69], v[218:221], v[202:205], v[66:69]
	s_setprio 0
	s_barrier
	s_mov_b32 m0, s43
	s_add_u32 s94, s34, 0x80
	s_addc_u32 s95, s35, 0
	global_load_lds_dwordx4 v146, s[34:35]
	s_mov_b32 m0, s44
	s_nop 0
	global_load_lds_dwordx4 v148, s[34:35]
	s_waitcnt vmcnt(8)
	s_barrier
	s_waitcnt lgkmcnt(0)
	s_setprio 1
	v_mfma_f32_16x16x32_bf16 v[62:65], v[126:129], v[226:229], v[62:65]
	ds_read_b128 v[158:161], v176 offset:32768
	v_mfma_f32_16x16x32_bf16 v[58:61], v[138:141], v[226:229], v[58:61]
	v_mfma_f32_16x16x32_bf16 v[54:57], v[126:129], v[234:237], v[54:57]
	ds_read_b128 v[178:181], v176 offset:33792
	v_mfma_f32_16x16x32_bf16 v[46:49], v[138:141], v[234:237], v[46:49]
	v_mfma_f32_16x16x32_bf16 v[38:41], v[126:129], v[242:245], v[38:41]
	ds_read_b128 v[182:185], v176 offset:34816
	v_mfma_f32_16x16x32_bf16 v[30:33], v[138:141], v[242:245], v[30:33]
	v_mfma_f32_16x16x32_bf16 v[22:25], v[126:129], v[250:253], v[22:25]
	ds_read_b128 v[186:189], v176 offset:35840
	v_mfma_f32_16x16x32_bf16 v[14:17], v[138:141], v[250:253], v[14:17]
	v_mfma_f32_16x16x32_bf16 v[62:65], v[134:137], v[230:233], v[62:65]
	ds_read_b128 v[190:193], v176 offset:36864
	v_mfma_f32_16x16x32_bf16 v[58:61], v[142:145], v[230:233], v[58:61]
	v_mfma_f32_16x16x32_bf16 v[54:57], v[134:137], v[238:241], v[54:57]
	ds_read_b128 v[194:197], v176 offset:37888
	v_mfma_f32_16x16x32_bf16 v[46:49], v[142:145], v[238:241], v[46:49]
	v_mfma_f32_16x16x32_bf16 v[38:41], v[134:137], v[246:249], v[38:41]
	ds_read_b128 v[198:201], v176 offset:38912
	v_mfma_f32_16x16x32_bf16 v[30:33], v[142:145], v[246:249], v[30:33]
	v_mfma_f32_16x16x32_bf16 v[22:25], v[134:137], v[222:225], v[22:25]
	ds_read_b128 v[202:205], v176 offset:39936
	v_mfma_f32_16x16x32_bf16 v[14:17], v[142:145], v[222:225], v[14:17]
	s_setprio 0
	s_barrier
	s_add_u32 s62, s30, 0x160000
	s_addc_u32 s63, s31, 0
	s_add_i32 s61, s52, s40
	s_mov_b32 m0, s61
	s_nop 0
	global_load_lds_dwordx4 v146, s[62:63]
	s_add_i32 m0, s61, 0x2000
	s_nop 0
	global_load_lds_dwordx4 v148, s[62:63]
	s_waitcnt vmcnt(10)
	s_barrier
	s_waitcnt lgkmcnt(0)
	s_setprio 1
	v_mfma_f32_16x16x32_bf16 v[50:53], v[206:209], v[226:229], v[50:53]
	ds_read_b128 v[126:129], v154
	v_mfma_f32_16x16x32_bf16 v[42:45], v[214:217], v[226:229], v[42:45]
	v_mfma_f32_16x16x32_bf16 v[34:37], v[206:209], v[234:237], v[34:37]
	v_mfma_f32_16x16x32_bf16 v[26:29], v[214:217], v[234:237], v[26:29]
	v_mfma_f32_16x16x32_bf16 v[18:21], v[206:209], v[242:245], v[18:21]
	ds_read_b128 v[134:137], v154 offset:1024
	v_mfma_f32_16x16x32_bf16 v[10:13], v[214:217], v[242:245], v[10:13]
	v_mfma_f32_16x16x32_bf16 v[6:9], v[206:209], v[250:253], v[6:9]
	v_mfma_f32_16x16x32_bf16 v[2:5], v[214:217], v[250:253], v[2:5]
	v_mfma_f32_16x16x32_bf16 v[50:53], v[210:213], v[230:233], v[50:53]
	ds_read_b128 v[138:141], v154 offset:2048
	v_mfma_f32_16x16x32_bf16 v[42:45], v[218:221], v[230:233], v[42:45]
	v_mfma_f32_16x16x32_bf16 v[34:37], v[210:213], v[238:241], v[34:37]
	v_mfma_f32_16x16x32_bf16 v[26:29], v[218:221], v[238:241], v[26:29]
	v_mfma_f32_16x16x32_bf16 v[18:21], v[210:213], v[246:249], v[18:21]
	ds_read_b128 v[142:145], v154 offset:3072
	v_mfma_f32_16x16x32_bf16 v[10:13], v[218:221], v[246:249], v[10:13]
	v_mfma_f32_16x16x32_bf16 v[6:9], v[210:213], v[222:225], v[6:9]
	v_mfma_f32_16x16x32_bf16 v[2:5], v[218:221], v[222:225], v[2:5]
	s_setprio 0
	s_barrier
	s_add_i32 s61, 0, 0x18000
	s_add_u32 s34, s34, 0x160000
	s_addc_u32 s35, s35, 0
	s_mov_b32 m0, s45
	s_nop 0
	global_load_lds_dwordx4 v146, s[34:35]
	s_mov_b32 m0, s46
	s_nop 0
	global_load_lds_dwordx4 v148, s[34:35]
	s_waitcnt vmcnt(10)
	s_barrier
	s_waitcnt lgkmcnt(0)
	s_setprio 1
	v_mfma_f32_16x16x32_bf16 v[130:133], v[126:129], v[158:161], v[130:133]
	ds_read_b128 v[206:209], v155
	v_mfma_f32_16x16x32_bf16 v[122:125], v[138:141], v[158:161], v[122:125]
	v_mfma_f32_16x16x32_bf16 v[118:121], v[126:129], v[182:185], v[118:121]
	v_mfma_f32_16x16x32_bf16 v[114:117], v[138:141], v[182:185], v[114:117]
	v_mfma_f32_16x16x32_bf16 v[102:105], v[126:129], v[190:193], v[102:105]
	ds_read_b128 v[210:213], v155 offset:1024
	v_mfma_f32_16x16x32_bf16 v[98:101], v[138:141], v[190:193], v[98:101]
	v_mfma_f32_16x16x32_bf16 v[86:89], v[126:129], v[198:201], v[86:89]
	v_mfma_f32_16x16x32_bf16 v[82:85], v[138:141], v[198:201], v[82:85]
	v_mfma_f32_16x16x32_bf16 v[130:133], v[134:137], v[178:181], v[130:133]
	ds_read_b128 v[214:217], v155 offset:2048
	v_mfma_f32_16x16x32_bf16 v[122:125], v[142:145], v[178:181], v[122:125]
	v_mfma_f32_16x16x32_bf16 v[118:121], v[134:137], v[186:189], v[118:121]
	v_mfma_f32_16x16x32_bf16 v[114:117], v[142:145], v[186:189], v[114:117]
	v_mfma_f32_16x16x32_bf16 v[102:105], v[134:137], v[194:197], v[102:105]
	ds_read_b128 v[218:221], v155 offset:3072
	v_mfma_f32_16x16x32_bf16 v[98:101], v[142:145], v[194:197], v[98:101]
	v_mfma_f32_16x16x32_bf16 v[86:89], v[134:137], v[202:205], v[86:89]
	v_mfma_f32_16x16x32_bf16 v[82:85], v[142:145], v[202:205], v[82:85]
	s_setprio 0
	s_barrier
	s_add_i32 s84, 0, 0x1c000
	s_add_i32 s85, s61, s40
	s_mov_b32 m0, s85
	s_nop 0
	global_load_lds_dwordx4 v146, s[96:97]
	s_add_i32 m0, s85, 0x2000
	s_nop 0
	global_load_lds_dwordx4 v148, s[96:97]
	s_waitcnt vmcnt(10)
	s_barrier
	s_waitcnt lgkmcnt(0)
	s_setprio 1
	v_mfma_f32_16x16x32_bf16 v[110:113], v[206:209], v[158:161], v[110:113]
	ds_read_b128 v[226:229], v176 offset:49152
	v_mfma_f32_16x16x32_bf16 v[106:109], v[214:217], v[158:161], v[106:109]
	v_mfma_f32_16x16x32_bf16 v[94:97], v[206:209], v[182:185], v[94:97]
	ds_read_b128 v[230:233], v176 offset:50176
	v_mfma_f32_16x16x32_bf16 v[90:93], v[214:217], v[182:185], v[90:93]
	v_mfma_f32_16x16x32_bf16 v[78:81], v[206:209], v[190:193], v[78:81]
	ds_read_b128 v[234:237], v176 offset:51200
	v_mfma_f32_16x16x32_bf16 v[74:77], v[214:217], v[190:193], v[74:77]
	v_mfma_f32_16x16x32_bf16 v[70:73], v[206:209], v[198:201], v[70:73]
	ds_read_b128 v[238:241], v176 offset:52224
	v_mfma_f32_16x16x32_bf16 v[66:69], v[214:217], v[198:201], v[66:69]
	v_mfma_f32_16x16x32_bf16 v[110:113], v[210:213], v[178:181], v[110:113]
	ds_read_b128 v[242:245], v176 offset:53248
	v_mfma_f32_16x16x32_bf16 v[106:109], v[218:221], v[178:181], v[106:109]
	v_mfma_f32_16x16x32_bf16 v[94:97], v[210:213], v[186:189], v[94:97]
	ds_read_b128 v[246:249], v176 offset:54272
	v_mfma_f32_16x16x32_bf16 v[90:93], v[218:221], v[186:189], v[90:93]
	v_mfma_f32_16x16x32_bf16 v[78:81], v[210:213], v[194:197], v[78:81]
	ds_read_b128 v[250:253], v176 offset:55296
	v_mfma_f32_16x16x32_bf16 v[74:77], v[218:221], v[194:197], v[74:77]
	v_mfma_f32_16x16x32_bf16 v[70:73], v[210:213], v[202:205], v[70:73]
	ds_read_b128 v[222:225], v176 offset:56320
	v_mfma_f32_16x16x32_bf16 v[66:69], v[218:221], v[202:205], v[66:69]
	s_setprio 0
	s_barrier
	s_mov_b32 m0, s48
	s_nop 0
	global_load_lds_dwordx4 v146, s[94:95]
	s_mov_b32 m0, s49
	s_nop 0
	global_load_lds_dwordx4 v148, s[94:95]
	s_waitcnt vmcnt(8)
	s_barrier
	s_waitcnt lgkmcnt(0)
	s_setprio 1
	v_mfma_f32_16x16x32_bf16 v[62:65], v[126:129], v[226:229], v[62:65]
	ds_read_b128 v[158:161], v176
	v_mfma_f32_16x16x32_bf16 v[58:61], v[138:141], v[226:229], v[58:61]
	v_mfma_f32_16x16x32_bf16 v[54:57], v[126:129], v[234:237], v[54:57]
	ds_read_b128 v[178:181], v176 offset:1024
	v_mfma_f32_16x16x32_bf16 v[46:49], v[138:141], v[234:237], v[46:49]
	v_mfma_f32_16x16x32_bf16 v[38:41], v[126:129], v[242:245], v[38:41]
	ds_read_b128 v[182:185], v176 offset:2048
	v_mfma_f32_16x16x32_bf16 v[30:33], v[138:141], v[242:245], v[30:33]
	v_mfma_f32_16x16x32_bf16 v[22:25], v[126:129], v[250:253], v[22:25]
	ds_read_b128 v[186:189], v176 offset:3072
	v_mfma_f32_16x16x32_bf16 v[14:17], v[138:141], v[250:253], v[14:17]
	v_mfma_f32_16x16x32_bf16 v[62:65], v[134:137], v[230:233], v[62:65]
	ds_read_b128 v[190:193], v176 offset:4096
	v_mfma_f32_16x16x32_bf16 v[58:61], v[142:145], v[230:233], v[58:61]
	v_mfma_f32_16x16x32_bf16 v[54:57], v[134:137], v[238:241], v[54:57]
	ds_read_b128 v[194:197], v176 offset:5120
	v_mfma_f32_16x16x32_bf16 v[46:49], v[142:145], v[238:241], v[46:49]
	v_mfma_f32_16x16x32_bf16 v[38:41], v[134:137], v[246:249], v[38:41]
	ds_read_b128 v[198:201], v176 offset:6144
	v_mfma_f32_16x16x32_bf16 v[30:33], v[142:145], v[246:249], v[30:33]
	v_mfma_f32_16x16x32_bf16 v[22:25], v[134:137], v[222:225], v[22:25]
	ds_read_b128 v[202:205], v176 offset:7168
	v_mfma_f32_16x16x32_bf16 v[14:17], v[142:145], v[222:225], v[14:17]
	s_setprio 0
	s_barrier
	s_add_u32 s30, s30, 0x160080
	s_addc_u32 s31, s31, 0
	s_add_i32 s84, s84, s40
	s_mov_b32 m0, s84
	s_nop 0
	global_load_lds_dwordx4 v146, s[30:31]
	s_add_i32 m0, s84, 0x2000
	s_nop 0
	global_load_lds_dwordx4 v148, s[30:31]
	s_waitcnt vmcnt(10)
	s_barrier
	s_waitcnt lgkmcnt(0)
	s_setprio 1
	v_mfma_f32_16x16x32_bf16 v[50:53], v[206:209], v[226:229], v[50:53]
	ds_read_b128 v[126:129], v175
	v_mfma_f32_16x16x32_bf16 v[42:45], v[214:217], v[226:229], v[42:45]
	v_mfma_f32_16x16x32_bf16 v[34:37], v[206:209], v[234:237], v[34:37]
	v_mfma_f32_16x16x32_bf16 v[26:29], v[214:217], v[234:237], v[26:29]
	v_mfma_f32_16x16x32_bf16 v[18:21], v[206:209], v[242:245], v[18:21]
	ds_read_b128 v[134:137], v175 offset:1024
	v_mfma_f32_16x16x32_bf16 v[10:13], v[214:217], v[242:245], v[10:13]
	v_mfma_f32_16x16x32_bf16 v[6:9], v[206:209], v[250:253], v[6:9]
	v_mfma_f32_16x16x32_bf16 v[2:5], v[214:217], v[250:253], v[2:5]
	v_mfma_f32_16x16x32_bf16 v[50:53], v[210:213], v[230:233], v[50:53]
	ds_read_b128 v[138:141], v175 offset:2048
	v_mfma_f32_16x16x32_bf16 v[42:45], v[218:221], v[230:233], v[42:45]
	v_mfma_f32_16x16x32_bf16 v[34:37], v[210:213], v[238:241], v[34:37]
	v_mfma_f32_16x16x32_bf16 v[26:29], v[218:221], v[238:241], v[26:29]
	v_mfma_f32_16x16x32_bf16 v[18:21], v[210:213], v[246:249], v[18:21]
	ds_read_b128 v[142:145], v175 offset:3072
	v_mfma_f32_16x16x32_bf16 v[10:13], v[218:221], v[246:249], v[10:13]
	v_mfma_f32_16x16x32_bf16 v[6:9], v[210:213], v[222:225], v[6:9]
	v_mfma_f32_16x16x32_bf16 v[2:5], v[218:221], v[222:225], v[2:5]
	s_setprio 0
	s_add_i32 s60, s60, 2
	s_add_u32 s28, s28, 0x100
	s_addc_u32 s29, s29, 0
	s_add_u32 s58, s58, 0x100
	s_addc_u32 s59, s59, 0
	s_cmpk_gt_u32 s60, 0x55
	s_barrier
	s_cbranch_scc0 .LBB0_1297
